# EpiVT epilogue regenerated: one token norm per lane per 128-token half + ds_bpermute gather (was 16 norms x 4 loads per lane, 16x redundant), SADDR stores; 900 -> 287 instrs
# speedup vs baseline: 1.0193x; 1.0098x over previous
.LBB0_239:
	s_lshl_b32 s0, s7, 8
	s_or_b32 s45, s0, s18
	s_lshl_b32 s1, s7, 6
	s_lshl_b32 s0, s8, 8
	s_and_b32 s1, s1, 0xfffffc00
	s_add_i32 s1, s1, s0
	v_and_b32_e32 v141, 31, v217
	v_or_b32_e32 v140, s45, v141
	v_lshlrev_b32_e32 v140, 6, v140
	global_load_dwordx4 v[160:163], v140, s[54:55] offset:48
	global_load_dwordx4 v[164:167], v140, s[54:55] offset:32
	global_load_dwordx4 v[168:171], v140, s[54:55] offset:16
	global_load_dwordx4 v[172:175], v140, s[54:55]
	v_add_u32_e32 v141, 0x2000, v140
	global_load_dwordx4 v[176:179], v141, s[54:55] offset:48
	global_load_dwordx4 v[180:183], v141, s[54:55] offset:32
	global_load_dwordx4 v[184:187], v141, s[54:55] offset:16
	global_load_dwordx4 v[228:231], v141, s[54:55]
	v_add_u32_e32 v142, s1, v152
	v_lshlrev_b32_e32 v157, 2, v155
	s_waitcnt vmcnt(4)
	v_add_f32_e32 v172, v172, v173
	v_add_f32_e32 v174, v174, v175
	v_add_f32_e32 v168, v168, v169
	v_add_f32_e32 v170, v170, v171
	v_add_f32_e32 v164, v164, v165
	v_add_f32_e32 v166, v166, v167
	v_add_f32_e32 v160, v160, v161
	v_add_f32_e32 v162, v162, v163
	v_add_f32_e32 v172, v172, v174
	v_add_f32_e32 v168, v168, v170
	v_add_f32_e32 v164, v164, v166
	v_add_f32_e32 v160, v160, v162
	v_add_f32_e32 v172, v172, v168
	v_add_f32_e32 v172, v172, v164
	v_add_f32_e32 v172, v172, v160
	v_fmamk_f32 v172, v172, 0x3a800000, v189
	v_cmp_gt_f32_e32 vcc, s13, v172
	v_mul_f32_e32 v173, 0x4b800000, v172
	s_nop 0
	v_cndmask_b32_e32 v172, v172, v173, vcc
	v_rsq_f32_e32 v172, v172
	s_nop 0
	v_mul_f32_e32 v173, 0x45800000, v172
	v_cndmask_b32_e32 v172, v172, v173, vcc
	ds_bpermute_b32 v208, v157, v172
	ds_bpermute_b32 v209, v157, v172 offset:4
	ds_bpermute_b32 v210, v157, v172 offset:8
	ds_bpermute_b32 v211, v157, v172 offset:12
	ds_bpermute_b32 v212, v157, v172 offset:32
	ds_bpermute_b32 v213, v157, v172 offset:36
	ds_bpermute_b32 v214, v157, v172 offset:40
	ds_bpermute_b32 v215, v157, v172 offset:44
	s_waitcnt vmcnt(0)
	v_add_f32_e32 v228, v228, v229
	v_add_f32_e32 v230, v230, v231
	v_add_f32_e32 v184, v184, v185
	v_add_f32_e32 v186, v186, v187
	v_add_f32_e32 v180, v180, v181
	v_add_f32_e32 v182, v182, v183
	v_add_f32_e32 v176, v176, v177
	v_add_f32_e32 v178, v178, v179
	v_add_f32_e32 v228, v228, v230
	v_add_f32_e32 v184, v184, v186
	v_add_f32_e32 v180, v180, v182
	v_add_f32_e32 v176, v176, v178
	v_add_f32_e32 v228, v228, v184
	v_add_f32_e32 v228, v228, v180
	v_add_f32_e32 v228, v228, v176
	v_fmamk_f32 v228, v228, 0x3a800000, v189
	v_cmp_gt_f32_e32 vcc, s13, v228
	v_mul_f32_e32 v229, 0x4b800000, v228
	s_nop 0
	v_cndmask_b32_e32 v228, v228, v229, vcc
	v_rsq_f32_e32 v228, v228
	s_nop 0
	v_mul_f32_e32 v229, 0x45800000, v228
	v_cndmask_b32_e32 v228, v228, v229, vcc
	ds_bpermute_b32 v232, v157, v228
	ds_bpermute_b32 v233, v157, v228 offset:4
	ds_bpermute_b32 v234, v157, v228 offset:8
	ds_bpermute_b32 v235, v157, v228 offset:12
	ds_bpermute_b32 v236, v157, v228 offset:32
	ds_bpermute_b32 v237, v157, v228 offset:36
	ds_bpermute_b32 v238, v157, v228 offset:40
	ds_bpermute_b32 v239, v157, v228 offset:44
	s_and_b32 s0, s45, 0xfe0
	v_or_b32_e32 v194, s0, v153
	v_lshlrev_b32_e32 v194, 1, v194
	s_waitcnt lgkmcnt(8)
	v_pk_mul_f32 v[124:125], v[124:125], v[208:209]
	v_pk_mul_f32 v[126:127], v[126:127], v[210:211]
	v_pk_mul_f32 v[120:121], v[120:121], v[212:213]
	v_pk_mul_f32 v[122:123], v[122:123], v[214:215]
	v_lshlrev_b32_e32 v140, 13, v142
	v_add_u32_e32 v140, v140, v194
	v_cvt_pk_bf16_f32 v124, v124, v125
	v_cvt_pk_bf16_f32 v125, v126, v127
	v_cvt_pk_bf16_f32 v126, v120, v121
	v_cvt_pk_bf16_f32 v127, v122, v123
	global_store_dwordx4 v140, v[124:127], s[66:67]
	v_pk_mul_f32 v[116:117], v[116:117], v[208:209]
	v_pk_mul_f32 v[118:119], v[118:119], v[210:211]
	v_pk_mul_f32 v[112:113], v[112:113], v[212:213]
	v_pk_mul_f32 v[114:115], v[114:115], v[214:215]
	v_add_u32_e32 v141, 0x10, v142
	v_lshlrev_b32_e32 v140, 13, v141
	v_add_u32_e32 v140, v140, v194
	v_cvt_pk_bf16_f32 v116, v116, v117
	v_cvt_pk_bf16_f32 v117, v118, v119
	v_cvt_pk_bf16_f32 v118, v112, v113
	v_cvt_pk_bf16_f32 v119, v114, v115
	global_store_dwordx4 v140, v[116:119], s[66:67]
	v_pk_mul_f32 v[108:109], v[108:109], v[208:209]
	v_pk_mul_f32 v[110:111], v[110:111], v[210:211]
	v_pk_mul_f32 v[104:105], v[104:105], v[212:213]
	v_pk_mul_f32 v[106:107], v[106:107], v[214:215]
	v_add_u32_e32 v141, 0x20, v142
	v_lshlrev_b32_e32 v140, 13, v141
	v_add_u32_e32 v140, v140, v194
	v_cvt_pk_bf16_f32 v108, v108, v109
	v_cvt_pk_bf16_f32 v109, v110, v111
	v_cvt_pk_bf16_f32 v110, v104, v105
	v_cvt_pk_bf16_f32 v111, v106, v107
	global_store_dwordx4 v140, v[108:111], s[66:67]
	v_pk_mul_f32 v[100:101], v[100:101], v[208:209]
	v_pk_mul_f32 v[102:103], v[102:103], v[210:211]
	v_pk_mul_f32 v[96:97], v[96:97], v[212:213]
	v_pk_mul_f32 v[98:99], v[98:99], v[214:215]
	v_add_u32_e32 v141, 0x30, v142
	v_lshlrev_b32_e32 v140, 13, v141
	v_add_u32_e32 v140, v140, v194
	v_cvt_pk_bf16_f32 v100, v100, v101
	v_cvt_pk_bf16_f32 v101, v102, v103
	v_cvt_pk_bf16_f32 v102, v96, v97
	v_cvt_pk_bf16_f32 v103, v98, v99
	global_store_dwordx4 v140, v[100:103], s[66:67]
	v_pk_mul_f32 v[92:93], v[92:93], v[208:209]
	v_pk_mul_f32 v[94:95], v[94:95], v[210:211]
	v_pk_mul_f32 v[88:89], v[88:89], v[212:213]
	v_pk_mul_f32 v[90:91], v[90:91], v[214:215]
	v_add_u32_e32 v141, 0x80, v142
	v_lshlrev_b32_e32 v140, 13, v141
	v_add_u32_e32 v140, v140, v194
	v_cvt_pk_bf16_f32 v92, v92, v93
	v_cvt_pk_bf16_f32 v93, v94, v95
	v_cvt_pk_bf16_f32 v94, v88, v89
	v_cvt_pk_bf16_f32 v95, v90, v91
	global_store_dwordx4 v140, v[92:95], s[66:67]
	v_pk_mul_f32 v[84:85], v[84:85], v[208:209]
	v_pk_mul_f32 v[86:87], v[86:87], v[210:211]
	v_pk_mul_f32 v[80:81], v[80:81], v[212:213]
	v_pk_mul_f32 v[82:83], v[82:83], v[214:215]
	v_add_u32_e32 v141, 0x90, v142
	v_lshlrev_b32_e32 v140, 13, v141
	v_add_u32_e32 v140, v140, v194
	v_cvt_pk_bf16_f32 v84, v84, v85
	v_cvt_pk_bf16_f32 v85, v86, v87
	v_cvt_pk_bf16_f32 v86, v80, v81
	v_cvt_pk_bf16_f32 v87, v82, v83
	global_store_dwordx4 v140, v[84:87], s[66:67]
	v_pk_mul_f32 v[76:77], v[76:77], v[208:209]
	v_pk_mul_f32 v[78:79], v[78:79], v[210:211]
	v_pk_mul_f32 v[72:73], v[72:73], v[212:213]
	v_pk_mul_f32 v[74:75], v[74:75], v[214:215]
	v_add_u32_e32 v141, 0xa0, v142
	v_lshlrev_b32_e32 v140, 13, v141
	v_add_u32_e32 v140, v140, v194
	v_cvt_pk_bf16_f32 v76, v76, v77
	v_cvt_pk_bf16_f32 v77, v78, v79
	v_cvt_pk_bf16_f32 v78, v72, v73
	v_cvt_pk_bf16_f32 v79, v74, v75
	global_store_dwordx4 v140, v[76:79], s[66:67]
	v_pk_mul_f32 v[68:69], v[68:69], v[208:209]
	v_pk_mul_f32 v[70:71], v[70:71], v[210:211]
	v_pk_mul_f32 v[64:65], v[64:65], v[212:213]
	v_pk_mul_f32 v[66:67], v[66:67], v[214:215]
	v_add_u32_e32 v141, 0xb0, v142
	v_lshlrev_b32_e32 v140, 13, v141
	v_add_u32_e32 v140, v140, v194
	v_cvt_pk_bf16_f32 v68, v68, v69
	v_cvt_pk_bf16_f32 v69, v70, v71
	v_cvt_pk_bf16_f32 v70, v64, v65
	v_cvt_pk_bf16_f32 v71, v66, v67
	global_store_dwordx4 v140, v[68:71], s[66:67]
	s_bitset1_b32 s45, 7
	s_and_b32 s0, s45, 0xfe0
	v_or_b32_e32 v194, s0, v153
	v_lshlrev_b32_e32 v194, 1, v194
	s_waitcnt lgkmcnt(0)
	v_pk_mul_f32 v[60:61], v[60:61], v[232:233]
	v_pk_mul_f32 v[62:63], v[62:63], v[234:235]
	v_pk_mul_f32 v[56:57], v[56:57], v[236:237]
	v_pk_mul_f32 v[58:59], v[58:59], v[238:239]
	v_lshlrev_b32_e32 v140, 13, v142
	v_add_u32_e32 v140, v140, v194
	v_cvt_pk_bf16_f32 v60, v60, v61
	v_cvt_pk_bf16_f32 v61, v62, v63
	v_cvt_pk_bf16_f32 v62, v56, v57
	v_cvt_pk_bf16_f32 v63, v58, v59
	global_store_dwordx4 v140, v[60:63], s[66:67]
	v_pk_mul_f32 v[52:53], v[52:53], v[232:233]
	v_pk_mul_f32 v[54:55], v[54:55], v[234:235]
	v_pk_mul_f32 v[48:49], v[48:49], v[236:237]
	v_pk_mul_f32 v[50:51], v[50:51], v[238:239]
	v_add_u32_e32 v141, 0x10, v142
	v_lshlrev_b32_e32 v140, 13, v141
	v_add_u32_e32 v140, v140, v194
	v_cvt_pk_bf16_f32 v52, v52, v53
	v_cvt_pk_bf16_f32 v53, v54, v55
	v_cvt_pk_bf16_f32 v54, v48, v49
	v_cvt_pk_bf16_f32 v55, v50, v51
	global_store_dwordx4 v140, v[52:55], s[66:67]
	v_pk_mul_f32 v[44:45], v[44:45], v[232:233]
	v_pk_mul_f32 v[46:47], v[46:47], v[234:235]
	v_pk_mul_f32 v[40:41], v[40:41], v[236:237]
	v_pk_mul_f32 v[42:43], v[42:43], v[238:239]
	v_add_u32_e32 v141, 0x20, v142
	v_lshlrev_b32_e32 v140, 13, v141
	v_add_u32_e32 v140, v140, v194
	v_cvt_pk_bf16_f32 v44, v44, v45
	v_cvt_pk_bf16_f32 v45, v46, v47
	v_cvt_pk_bf16_f32 v46, v40, v41
	v_cvt_pk_bf16_f32 v47, v42, v43
	global_store_dwordx4 v140, v[44:47], s[66:67]
	v_pk_mul_f32 v[36:37], v[36:37], v[232:233]
	v_pk_mul_f32 v[38:39], v[38:39], v[234:235]
	v_pk_mul_f32 v[32:33], v[32:33], v[236:237]
	v_pk_mul_f32 v[34:35], v[34:35], v[238:239]
	v_add_u32_e32 v141, 0x30, v142
	v_lshlrev_b32_e32 v140, 13, v141
	v_add_u32_e32 v140, v140, v194
	v_cvt_pk_bf16_f32 v36, v36, v37
	v_cvt_pk_bf16_f32 v37, v38, v39
	v_cvt_pk_bf16_f32 v38, v32, v33
	v_cvt_pk_bf16_f32 v39, v34, v35
	global_store_dwordx4 v140, v[36:39], s[66:67]
	v_pk_mul_f32 v[28:29], v[28:29], v[232:233]
	v_pk_mul_f32 v[30:31], v[30:31], v[234:235]
	v_pk_mul_f32 v[24:25], v[24:25], v[236:237]
	v_pk_mul_f32 v[26:27], v[26:27], v[238:239]
	v_add_u32_e32 v141, 0x80, v142
	v_lshlrev_b32_e32 v140, 13, v141
	v_add_u32_e32 v140, v140, v194
	v_cvt_pk_bf16_f32 v28, v28, v29
	v_cvt_pk_bf16_f32 v29, v30, v31
	v_cvt_pk_bf16_f32 v30, v24, v25
	v_cvt_pk_bf16_f32 v31, v26, v27
	global_store_dwordx4 v140, v[28:31], s[66:67]
	v_pk_mul_f32 v[20:21], v[20:21], v[232:233]
	v_pk_mul_f32 v[22:23], v[22:23], v[234:235]
	v_pk_mul_f32 v[16:17], v[16:17], v[236:237]
	v_pk_mul_f32 v[18:19], v[18:19], v[238:239]
	v_add_u32_e32 v141, 0x90, v142
	v_lshlrev_b32_e32 v140, 13, v141
	v_add_u32_e32 v140, v140, v194
	v_cvt_pk_bf16_f32 v20, v20, v21
	v_cvt_pk_bf16_f32 v21, v22, v23
	v_cvt_pk_bf16_f32 v22, v16, v17
	v_cvt_pk_bf16_f32 v23, v18, v19
	global_store_dwordx4 v140, v[20:23], s[66:67]
	v_pk_mul_f32 v[12:13], v[12:13], v[232:233]
	v_pk_mul_f32 v[14:15], v[14:15], v[234:235]
	v_pk_mul_f32 v[8:9], v[8:9], v[236:237]
	v_pk_mul_f32 v[10:11], v[10:11], v[238:239]
	v_add_u32_e32 v141, 0xa0, v142
	v_lshlrev_b32_e32 v140, 13, v141
	v_add_u32_e32 v140, v140, v194
	v_cvt_pk_bf16_f32 v12, v12, v13
	v_cvt_pk_bf16_f32 v13, v14, v15
	v_cvt_pk_bf16_f32 v14, v8, v9
	v_cvt_pk_bf16_f32 v15, v10, v11
	global_store_dwordx4 v140, v[12:15], s[66:67]
	v_pk_mul_f32 v[4:5], v[4:5], v[232:233]
	v_pk_mul_f32 v[6:7], v[6:7], v[234:235]
	v_pk_mul_f32 v[0:1], v[0:1], v[236:237]
	v_pk_mul_f32 v[2:3], v[2:3], v[238:239]
	v_add_u32_e32 v141, 0xb0, v142
	v_lshlrev_b32_e32 v140, 13, v141
	v_add_u32_e32 v140, v140, v194
	v_cvt_pk_bf16_f32 v4, v4, v5
	v_cvt_pk_bf16_f32 v5, v6, v7
	v_cvt_pk_bf16_f32 v6, v0, v1
	v_cvt_pk_bf16_f32 v7, v2, v3
	global_store_dwordx4 v140, v[4:7], s[66:67]
	s_mov_b64 s[0:1], -1
	s_andn2_b64 vcc, exec, s[38:39]
	s_cbranch_vccnz .LBB0_228
	s_andn2_b64 vcc, exec, s[36:37]
	s_cbranch_vccnz .LBB0_227
	s_barrier
	s_branch .LBB0_227
